# rwb closed-form decay exponent + LDS-staged w0/a0 rows, plus the wave stagger of the previous version
# speedup vs baseline: 1.0104x; 1.0104x over previous
; __device__ __forceinline__ float tanhf_(float x) { const float e = __expf(2.0f * fminf(fmaxf(x, -15.f), 15.f)); return (e - 1.0f) * __builtin_amdgcn_rcpf(e + 1.0f); }
; __device__ __forceinline__ void phase_rwb(const int wvs, const Params& p, LAS unsigned char* lds, int layer) {
;     ...
;   for (int d = 0; d < 2; ++d) {
;     h8 bw[2], ba[2];
; #pragma unroll
;     for (int ks = 0; ks < 2; ++ks) { const h8 x = *(const h8*)(P + tok * PP + PC_RL2 + d * 64 + ks * 32 + fq * 8);
; #pragma unroll
;       for (int j = 0; j < 8; ++j) bw[ks][j] = (hf)tanhf_((float)x[j]);
;       ba[ks] = *(const h8*)(P + tok * PP + PC_RL2 + 128 + d * 64 + ks * 32 + fq * 8); }
;     { h8 sw[6], sa[6];
; #pragma unroll
;       for (int j = 0; j < 6; ++j) { const int idx = tid + 512 * j; const size_t wo = ((size_t)d * 384 + (idx >> 3)) * 64 + (idx & 7) * 8; sw[j] = *(const h8*)(wupT + wo); sa[j] = *(const h8*)(aupT + wo); }
;       __syncthreads();
.LBB0_1145:
	s_lshl_b32 s30, s6, 7
	v_lshl_add_u64 v[14:15], v[66:67], 0, s[30:31]
	global_load_dwordx4 v[2:5], v[14:15], off offset:3584
	s_mul_i32 s30, s6, 0x180
	v_lshl_add_u64 v[26:27], s[30:31], 0, v[70:71]
	v_lshlrev_b64 v[30:31], 7, v[26:27]
	v_or_b32_e32 v30, v30, v0
	v_lshl_add_u64 v[34:35], s[30:31], 0, v[72:73]
	v_lshl_add_u64 v[26:27], s[8:9], 0, v[30:31]
	v_lshlrev_b64 v[38:39], 7, v[34:35]
	v_lshl_add_u64 v[30:31], s[10:11], 0, v[30:31]
	v_or_b32_e32 v38, v38, v0
	v_lshl_add_u64 v[42:43], s[30:31], 0, v[74:75]
	v_lshl_add_u64 v[34:35], s[8:9], 0, v[38:39]
	v_lshlrev_b64 v[46:47], 7, v[42:43]
	v_lshl_add_u64 v[38:39], s[10:11], 0, v[38:39]
	v_or_b32_e32 v46, v46, v0
	v_lshl_add_u64 v[50:51], s[30:31], 0, v[76:77]
	v_lshl_add_u64 v[42:43], s[8:9], 0, v[46:47]
	v_lshlrev_b64 v[54:55], 7, v[50:51]
	v_lshl_add_u64 v[46:47], s[10:11], 0, v[46:47]
	v_or_b32_e32 v54, v54, v0
	v_lshl_add_u64 v[58:59], s[30:31], 0, v[78:79]
	v_lshl_add_u64 v[50:51], s[8:9], 0, v[54:55]
	v_lshlrev_b64 v[62:63], 7, v[58:59]
	v_lshl_add_u64 v[54:55], s[10:11], 0, v[54:55]
	v_or_b32_e32 v62, v62, v0
	v_lshl_add_u64 v[58:59], s[8:9], 0, v[62:63]
	v_lshl_add_u64 v[62:63], s[10:11], 0, v[62:63]
	s_or_b32 s2, s6, s16
	s_xor_b64 s[12:13], s[4:5], -1
	s_mov_b64 s[14:15], 0
	s_waitcnt vmcnt(0)
	v_cvt_f32_f16_e32 v6, v2
	v_cvt_f32_f16_sdwa v2, v2 dst_sel:DWORD dst_unused:UNUSED_PAD src0_sel:WORD_1
	v_med3_f32 v6, v6, s70, v223
	v_add_f32_e32 v6, v6, v6
	v_mul_f32_e32 v6, 0x3fb8aa3b, v6
	v_exp_f32_e32 v6, v6
	v_med3_f32 v2, v2, s70, v223
	v_add_f32_e32 v2, v2, v2
	v_mul_f32_e32 v2, 0x3fb8aa3b, v2
	v_add_f32_e32 v7, 1.0, v6
	v_rcp_f32_e32 v8, v7
	v_exp_f32_e32 v7, v2
	s_nop 0
	v_add_f32_e32 v2, 1.0, v7
	v_rcp_f32_e32 v9, v2
	v_pk_add_f32 v[6:7], v[6:7], -1.0 op_sel_hi:[1,0]
	s_nop 0
	v_pk_mul_f32 v[6:7], v[6:7], v[8:9]
	s_nop 0
	v_cvt_pk_f16_f32 v2, v6, v7
	v_cvt_f32_f16_e32 v6, v3
	v_cvt_f32_f16_sdwa v3, v3 dst_sel:DWORD dst_unused:UNUSED_PAD src0_sel:WORD_1
	v_med3_f32 v6, v6, s70, v223
	v_add_f32_e32 v6, v6, v6
	v_mul_f32_e32 v6, 0x3fb8aa3b, v6
	v_exp_f32_e32 v6, v6
	v_med3_f32 v3, v3, s70, v223
	v_add_f32_e32 v3, v3, v3
	v_mul_f32_e32 v3, 0x3fb8aa3b, v3
	v_add_f32_e32 v7, 1.0, v6
	v_rcp_f32_e32 v8, v7
	v_exp_f32_e32 v7, v3
	s_nop 0
	v_add_f32_e32 v3, 1.0, v7
	v_rcp_f32_e32 v9, v3
	v_pk_add_f32 v[6:7], v[6:7], -1.0 op_sel_hi:[1,0]
	s_nop 0
	v_pk_mul_f32 v[6:7], v[6:7], v[8:9]
	s_nop 0
	v_cvt_pk_f16_f32 v3, v6, v7
	v_cvt_f32_f16_e32 v6, v4
	v_cvt_f32_f16_sdwa v4, v4 dst_sel:DWORD dst_unused:UNUSED_PAD src0_sel:WORD_1
	v_med3_f32 v6, v6, s70, v223
	v_add_f32_e32 v6, v6, v6
	v_mul_f32_e32 v6, 0x3fb8aa3b, v6
	v_exp_f32_e32 v6, v6
	v_med3_f32 v4, v4, s70, v223
	v_add_f32_e32 v4, v4, v4
	v_mul_f32_e32 v4, 0x3fb8aa3b, v4
	v_add_f32_e32 v7, 1.0, v6
	v_rcp_f32_e32 v8, v7
	v_exp_f32_e32 v7, v4
	s_nop 0
	v_add_f32_e32 v4, 1.0, v7
	v_rcp_f32_e32 v9, v4
	v_pk_add_f32 v[6:7], v[6:7], -1.0 op_sel_hi:[1,0]
	s_nop 0
	v_pk_mul_f32 v[6:7], v[6:7], v[8:9]
	s_nop 0
	v_cvt_pk_f16_f32 v4, v6, v7
	v_cvt_f32_f16_e32 v6, v5
	v_cvt_f32_f16_sdwa v5, v5 dst_sel:DWORD dst_unused:UNUSED_PAD src0_sel:WORD_1
	v_med3_f32 v6, v6, s70, v223
	v_add_f32_e32 v6, v6, v6
	v_mul_f32_e32 v6, 0x3fb8aa3b, v6
	v_exp_f32_e32 v6, v6
	v_med3_f32 v5, v5, s70, v223
	v_add_f32_e32 v5, v5, v5
	v_mul_f32_e32 v5, 0x3fb8aa3b, v5
	v_add_f32_e32 v7, 1.0, v6
	v_rcp_f32_e32 v8, v7
	v_exp_f32_e32 v7, v5
	s_nop 0
	v_add_f32_e32 v5, 1.0, v7
	v_rcp_f32_e32 v9, v5
	v_pk_add_f32 v[6:7], v[6:7], -1.0 op_sel_hi:[1,0]
	s_nop 0
	v_pk_mul_f32 v[6:7], v[6:7], v[8:9]
	s_nop 0
	v_cvt_pk_f16_f32 v5, v6, v7
	global_load_dwordx4 v[6:9], v[14:15], off offset:3840
	global_load_dwordx4 v[10:13], v[14:15], off offset:3648
	s_waitcnt vmcnt(0)
	v_cvt_f32_f16_e32 v16, v10
	v_cvt_f32_f16_sdwa v10, v10 dst_sel:DWORD dst_unused:UNUSED_PAD src0_sel:WORD_1
	global_load_dwordx4 v[30:33], v[30:31], off
	v_med3_f32 v16, v16, s70, v223
	v_add_f32_e32 v16, v16, v16
	v_mul_f32_e32 v16, 0x3fb8aa3b, v16
	v_exp_f32_e32 v16, v16
	v_med3_f32 v10, v10, s70, v223
	v_add_f32_e32 v10, v10, v10
	v_mul_f32_e32 v10, 0x3fb8aa3b, v10
	v_add_f32_e32 v17, 1.0, v16
	v_rcp_f32_e32 v18, v17
	v_exp_f32_e32 v17, v10
	global_load_dwordx4 v[34:37], v[34:35], off
	v_add_f32_e32 v10, 1.0, v17
	v_rcp_f32_e32 v19, v10
	v_pk_add_f32 v[16:17], v[16:17], -1.0 op_sel_hi:[1,0]
	global_load_dwordx4 v[38:41], v[38:39], off
	v_pk_mul_f32 v[16:17], v[16:17], v[18:19]
	s_nop 0
	v_cvt_pk_f16_f32 v10, v16, v17
	v_cvt_f32_f16_e32 v16, v11
	v_cvt_f32_f16_sdwa v11, v11 dst_sel:DWORD dst_unused:UNUSED_PAD src0_sel:WORD_1
	global_load_dwordx4 v[42:45], v[42:43], off
	v_med3_f32 v16, v16, s70, v223
	v_add_f32_e32 v16, v16, v16
	v_mul_f32_e32 v16, 0x3fb8aa3b, v16
	v_exp_f32_e32 v16, v16
	v_med3_f32 v11, v11, s70, v223
	v_add_f32_e32 v11, v11, v11
	v_mul_f32_e32 v11, 0x3fb8aa3b, v11
	v_add_f32_e32 v17, 1.0, v16
	v_rcp_f32_e32 v18, v17
	v_exp_f32_e32 v17, v11
	global_load_dwordx4 v[46:49], v[46:47], off
	v_add_f32_e32 v11, 1.0, v17
	v_rcp_f32_e32 v19, v11
	v_pk_add_f32 v[16:17], v[16:17], -1.0 op_sel_hi:[1,0]
	global_load_dwordx4 v[50:53], v[50:51], off
	v_pk_mul_f32 v[16:17], v[16:17], v[18:19]
	s_nop 0
	v_cvt_pk_f16_f32 v11, v16, v17
	v_cvt_f32_f16_e32 v16, v12
	v_cvt_f32_f16_sdwa v12, v12 dst_sel:DWORD dst_unused:UNUSED_PAD src0_sel:WORD_1
	global_load_dwordx4 v[54:57], v[54:55], off
	v_med3_f32 v16, v16, s70, v223
	v_add_f32_e32 v16, v16, v16
	v_mul_f32_e32 v16, 0x3fb8aa3b, v16
	v_exp_f32_e32 v16, v16
	v_med3_f32 v12, v12, s70, v223
	v_add_f32_e32 v12, v12, v12
	v_mul_f32_e32 v12, 0x3fb8aa3b, v12
	v_add_f32_e32 v17, 1.0, v16
	v_rcp_f32_e32 v18, v17
	v_exp_f32_e32 v17, v12
	global_load_dwordx4 v[58:61], v[58:59], off
	v_add_f32_e32 v12, 1.0, v17
	v_rcp_f32_e32 v19, v12
	v_pk_add_f32 v[16:17], v[16:17], -1.0 op_sel_hi:[1,0]
	global_load_dwordx4 v[62:65], v[62:63], off
	v_pk_mul_f32 v[16:17], v[16:17], v[18:19]
	s_nop 0
	v_cvt_pk_f16_f32 v12, v16, v17
	v_cvt_f32_f16_e32 v16, v13
	v_cvt_f32_f16_sdwa v13, v13 dst_sel:DWORD dst_unused:UNUSED_PAD src0_sel:WORD_1
	global_load_dwordx4 v[26:29], v[26:27], off
	v_med3_f32 v16, v16, s70, v223
	v_add_f32_e32 v16, v16, v16
	v_mul_f32_e32 v16, 0x3fb8aa3b, v16
	v_exp_f32_e32 v16, v16
	v_med3_f32 v13, v13, s70, v223
	v_add_f32_e32 v13, v13, v13
	v_mul_f32_e32 v13, 0x3fb8aa3b, v13
	v_add_f32_e32 v17, 1.0, v16
	v_rcp_f32_e32 v18, v17
	v_exp_f32_e32 v17, v13
	s_nop 0
	v_add_f32_e32 v13, 1.0, v17
	v_rcp_f32_e32 v19, v13
	v_pk_add_f32 v[16:17], v[16:17], -1.0 op_sel_hi:[1,0]
	s_nop 0
	v_pk_mul_f32 v[16:17], v[16:17], v[18:19]
	v_lshl_add_u64 v[18:19], s[30:31], 0, v[68:69]
	v_lshlrev_b64 v[22:23], 7, v[18:19]
	v_or_b32_e32 v22, v22, v0
	v_lshl_add_u64 v[18:19], s[8:9], 0, v[22:23]
	v_cvt_pk_f16_f32 v13, v16, v17
	global_load_dwordx4 v[14:17], v[14:15], off offset:3904
	v_lshl_add_u64 v[22:23], s[10:11], 0, v[22:23]
	global_load_dwordx4 v[18:21], v[18:19], off
	s_mul_i32 s30, s2, 0x180
	global_load_dwordx4 v[22:25], v[22:23], off
	s_barrier
; #define LAS __attribute__((address_space(3)))
; __device__ __forceinline__ float sigmoidf_(float x) { return __builtin_amdgcn_rcpf(1.0f + __expf(-x)); }
; __device__ __forceinline__ float softplusf_(float x) { return x > 20.f ? x : __logf(1.0f + __expf(x)); }
; __device__ __forceinline__ f32x4 mfma16(h8 a, h8 b, f32x4 c) { return __builtin_amdgcn_mfma_f32_16x16x32_f16(a, b, c, 0, 0, 0); }
; __device__ __forceinline__ void phase_rwb(const int wvs, const Params& p, LAS unsigned char* lds, int layer) {
;     ...
;       __syncthreads();
; #pragma unroll
;       for (int j = 0; j < 6; ++j) { const int idx = tid + 512 * j; *(LAS h8*)(lds + (idx >> 3) * 144 + (idx & 7) * 16) = sw[j]; *(LAS h8*)(lds + 55296 + (idx >> 3) * 144 + (idx & 7) * 16) = sa[j]; }
;       __syncthreads(); }
;     const float* w0 = p.in[I_W0] + (layer * 2 + d) * 384; const float* a0 = p.in[I_A0] + (layer * 2 + d) * 384;
; #pragma unroll 2
;     for (int nt = 0; nt < 24; ++nt) { f32x4 aw = {0.f, 0.f, 0.f, 0.f}, aa = {0.f, 0.f, 0.f, 0.f};
;       const int n4 = nt * 16 + fq * 4; const f32x4 w04 = *(const f32x4*)(w0 + n4), a04 = *(const f32x4*)(a0 + n4);
; #pragma unroll
;       for (int ks = 0; ks < 2; ++ks) { aw = mfma16(*(const LAS h8*)(lds + (nt * 16 + fr) * 144 + ks * 64 + fq * 16), bw[ks], aw); aa = mfma16(*(const LAS h8*)(lds + 55296 + (nt * 16 + fr) * 144 + ks * 64 + fq * 16), ba[ks], aa); }
;       h4 oe, oa;
; #pragma unroll
;       for (int r = 0; r < 4; ++r) { const float wl = -softplusf_(-(w04[r] + aw[r])) - 0.5f; oe[r] = (hf)__expf(wl); oa[r] = (hf)sigmoidf_(a04[r] + aa[r]); }
;       *(h4*)(P + tok * PP + PC_EF + d * 384 + n4) = oe; *(h4*)(P + tok * PP + PC_AF + d * 384 + n4) = oa; }
	s_waitcnt vmcnt(1)
	ds_write_b128 v87, v[18:21]
	s_waitcnt vmcnt(0)
	ds_write_b128 v87, v[22:25] offset:55296
	ds_write_b128 v88, v[26:29]
	ds_write_b128 v88, v[30:33] offset:55296
	ds_write_b128 v89, v[34:37]
	ds_write_b128 v89, v[38:41] offset:55296
	ds_write_b128 v90, v[42:45]
	ds_write_b128 v90, v[46:49] offset:55296
	ds_write_b128 v91, v[50:53]
	ds_write_b128 v91, v[54:57] offset:55296
	ds_write_b128 v92, v[58:61]
	ds_write_b128 v92, v[62:65] offset:55296
	v_mov_b32_e32 v18, 0x300
	v_mad_u64_u32 v[26:27], s[4:5], s6, v18, v[80:81]
	s_lshl_b64 s[4:5], s[30:31], 2
	s_nop 0
	v_lshl_add_u64 v[28:29], v[82:83], 0, s[4:5]
	v_lshl_add_u64 v[30:31], v[84:85], 0, s[4:5]
	v_mov_b32_e32 v32, v86
	v_readfirstlane_b32 s4, v30
	v_readfirstlane_b32 s5, v31
	v_min_u32_e32 v104, 0x5f, v193
	v_lshlrev_b32_e32 v104, 4, v104
	v_and_b32_e32 v106, 48, v193
	v_add_u32_e32 v105, 0x1b800, v104
	v_add_u32_e32 v106, 0x1b800, v106
	s_nop 1
	global_load_dwordx4 v[96:99], v104, s[4:5]
	v_readfirstlane_b32 s4, v28
	v_readfirstlane_b32 s5, v29
	s_nop 4
	global_load_dwordx4 v[100:103], v104, s[4:5]
	s_waitcnt vmcnt(0)
	ds_write_b128 v105, v[96:99]
	ds_write_b128 v105, v[100:103] offset:1536
	s_waitcnt lgkmcnt(0)
	s_barrier
	v_readfirstlane_b32 s4, v193
	s_nop 0
	s_cmp_lt_u32 s4, 0x100
	s_cbranch_scc1 .Lrwb_go
	s_sleep 8
.Lrwb_go:
.LBB0_1146:
	ds_read_b128 v[18:21], v106
	ds_read_b128 v[22:25], v106 offset:1536
	ds_read_b128 v[34:37], v32
	ds_read_b128 v[42:45], v32 offset:64
	ds_read_b128 v[38:41], v32 offset:55296
	s_add_u32 s14, s14, 0x80
	s_addc_u32 s15, s15, 0
	s_waitcnt lgkmcnt(2)
	v_mfma_f32_16x16x32_f16 v[34:37], v[34:37], v[2:5], 0
	s_cmpk_eq_i32 s14, 0x600
	s_waitcnt lgkmcnt(1)
	v_mfma_f32_16x16x32_f16 v[34:37], v[42:45], v[10:13], v[34:37]
	ds_read_b128 v[42:45], v32 offset:55360
	s_waitcnt lgkmcnt(1)
	v_mfma_f32_16x16x32_f16 v[38:41], v[38:41], v[6:9], 0
	s_waitcnt lgkmcnt(0)
	v_mfma_f32_16x16x32_f16 v[38:41], v[42:45], v[14:17], v[38:41]
	s_nop 0
	s_nop 1
	v_add_f32_e32 v18, v18, v34
	v_add_f32_e32 v19, v19, v35
	v_add_f32_e32 v20, v20, v36
	v_add_f32_e32 v21, v21, v37
	v_mul_f32_e32 v18, 0xbfb8aa3b, v18
	v_mul_f32_e32 v19, 0xbfb8aa3b, v19
	v_mul_f32_e32 v20, 0xbfb8aa3b, v20
	v_mul_f32_e32 v21, 0xbfb8aa3b, v21
	v_exp_f32_e32 v18, v18
	v_exp_f32_e32 v19, v19
	v_exp_f32_e32 v20, v20
	v_exp_f32_e32 v21, v21
	v_add_f32_e32 v18, 1.0, v18
	v_add_f32_e32 v19, 1.0, v19
	v_add_f32_e32 v20, 1.0, v20
	v_add_f32_e32 v21, 1.0, v21
	v_add_f32_e32 v22, v22, v38
	v_add_f32_e32 v23, v23, v39
	v_add_f32_e32 v24, v24, v40
	v_add_f32_e32 v25, v25, v41
	v_mul_f32_e32 v22, 0xbfb8aa3b, v22
	v_mul_f32_e32 v23, 0xbfb8aa3b, v23
	v_mul_f32_e32 v24, 0xbfb8aa3b, v24
	v_mul_f32_e32 v25, 0xbfb8aa3b, v25
	v_exp_f32_e32 v22, v22
	v_exp_f32_e32 v23, v23
	v_exp_f32_e32 v24, v24
	v_exp_f32_e32 v25, v25
	v_rcp_f32_e32 v18, v18
	v_rcp_f32_e32 v19, v19
	v_rcp_f32_e32 v20, v20
	v_rcp_f32_e32 v21, v21
	v_add_f32_e32 v22, 1.0, v22
	v_add_f32_e32 v23, 1.0, v23
	v_add_f32_e32 v24, 1.0, v24
	v_add_f32_e32 v25, 1.0, v25
	v_rcp_f32_e32 v22, v22
	v_rcp_f32_e32 v23, v23
	v_rcp_f32_e32 v24, v24
	v_rcp_f32_e32 v25, v25
	v_mul_f32_e32 v18, 0x3f1b4598, v18
	v_mul_f32_e32 v19, 0x3f1b4598, v19
	v_mul_f32_e32 v20, 0x3f1b4598, v20
	v_mul_f32_e32 v21, 0x3f1b4598, v21
	v_cvt_pk_f16_f32 v18, v18, v19
	v_cvt_pk_f16_f32 v19, v20, v21
	v_cvt_pk_f16_f32 v20, v22, v23
	v_cvt_pk_f16_f32 v21, v24, v25
	global_store_dwordx2 v[26:27], v[18:19], off offset:-1536
	global_store_dwordx2 v[26:27], v[20:21], off
	ds_read_b128 v[22:25], v106 offset:64
	ds_read_b128 v[18:21], v106 offset:1600
	ds_read_b128 v[34:37], v32 offset:2304
	ds_read_b128 v[42:45], v32 offset:2368
	s_waitcnt lgkmcnt(1)
	v_mfma_f32_16x16x32_f16 v[34:37], v[34:37], v[2:5], 0
	ds_read_b128 v[38:41], v32 offset:57600
	s_waitcnt lgkmcnt(1)
	v_mfma_f32_16x16x32_f16 v[34:37], v[42:45], v[10:13], v[34:37]
	ds_read_b128 v[42:45], v32 offset:57664
	v_add_u32_e32 v32, 0x1200, v32
	s_waitcnt lgkmcnt(1)
	v_mfma_f32_16x16x32_f16 v[38:41], v[38:41], v[6:9], 0
	s_nop 0
	s_nop 2
	v_add_f32_e32 v22, v22, v34
	v_add_f32_e32 v23, v23, v35
	v_add_f32_e32 v24, v24, v36
	v_add_f32_e32 v25, v25, v37
	s_waitcnt lgkmcnt(0)
	v_mfma_f32_16x16x32_f16 v[38:41], v[42:45], v[14:17], v[38:41]
	v_mul_f32_e32 v22, 0xbfb8aa3b, v22
	v_mul_f32_e32 v23, 0xbfb8aa3b, v23
	v_mul_f32_e32 v24, 0xbfb8aa3b, v24
	v_mul_f32_e32 v25, 0xbfb8aa3b, v25
	v_exp_f32_e32 v22, v22
	v_exp_f32_e32 v23, v23
	v_exp_f32_e32 v24, v24
	v_exp_f32_e32 v25, v25
	v_add_f32_e32 v22, 1.0, v22
	v_add_f32_e32 v23, 1.0, v23
	v_add_f32_e32 v24, 1.0, v24
	v_add_f32_e32 v25, 1.0, v25
	v_add_f32_e32 v38, v18, v38
	v_add_f32_e32 v39, v19, v39
	v_add_f32_e32 v40, v20, v40
	v_add_f32_e32 v41, v21, v41
	v_mul_f32_e32 v38, 0xbfb8aa3b, v38
	v_mul_f32_e32 v39, 0xbfb8aa3b, v39
	v_mul_f32_e32 v40, 0xbfb8aa3b, v40
	v_mul_f32_e32 v41, 0xbfb8aa3b, v41
	v_exp_f32_e32 v38, v38
	v_exp_f32_e32 v39, v39
	v_exp_f32_e32 v40, v40
	v_exp_f32_e32 v41, v41
	v_rcp_f32_e32 v22, v22
	v_rcp_f32_e32 v23, v23
	v_rcp_f32_e32 v24, v24
	v_rcp_f32_e32 v25, v25
	v_add_f32_e32 v38, 1.0, v38
	v_add_f32_e32 v39, 1.0, v39
	v_add_f32_e32 v40, 1.0, v40
	v_add_f32_e32 v41, 1.0, v41
	v_rcp_f32_e32 v38, v38
	v_rcp_f32_e32 v39, v39
	v_rcp_f32_e32 v40, v40
	v_rcp_f32_e32 v41, v41
	v_mul_f32_e32 v22, 0x3f1b4598, v22
	v_mul_f32_e32 v23, 0x3f1b4598, v23
	v_mul_f32_e32 v24, 0x3f1b4598, v24
	v_mul_f32_e32 v25, 0x3f1b4598, v25
	v_cvt_pk_f16_f32 v18, v22, v23
	v_cvt_pk_f16_f32 v19, v24, v25
	v_cvt_pk_f16_f32 v20, v38, v39
	v_cvt_pk_f16_f32 v21, v40, v41
	global_store_dwordx2 v[26:27], v[18:19], off offset:-1504
	global_store_dwordx2 v[26:27], v[20:21], off offset:32
	v_lshl_add_u64 v[26:27], v[26:27], 0, 64
	v_add_u32_e32 v106, 0x80, v106
	s_cbranch_scc0 .LBB0_1146
	s_mov_b32 s6, 1
	s_mov_b64 s[4:5], 0
	s_and_b64 vcc, exec, s[12:13]
	s_cbranch_vccz .LBB0_1145
